# convert phase input-row units de-serialised (scale/shift hoisted, 8 row loads batched) on top of fin loop changes
# speedup vs baseline: 1.0395x; 1.0001x over previous
.LBB0_630:
	global_load_dwordx4 v[104:107], v[4:5], off
	global_load_dwordx4 v[108:111], v[4:5], off offset:16
	global_load_dwordx4 v[112:115], v[2:3], off
	global_load_dwordx4 v[116:119], v[2:3], off offset:16
	v_ashrrev_i32_e32 v40, 7, v14
	v_ashrrev_i32_e32 v41, 31, v40
	v_lshlrev_b64 v[16:17], 12, v[40:41]
	v_lshl_add_u64 v[20:21], v[0:1], 0, v[16:17]
	s_mov_b64 s[14:15], 0x2000
	global_load_dwordx4 v[166:169], v[20:21], off
	global_load_dwordx4 v[170:173], v[20:21], off offset:16
	v_lshl_add_u64 v[20:21], v[20:21], 0, s[14:15]
	global_load_dwordx4 v[174:177], v[20:21], off
	global_load_dwordx4 v[178:181], v[20:21], off offset:16
	v_lshl_add_u64 v[20:21], v[20:21], 0, s[14:15]
	global_load_dwordx4 v[182:185], v[20:21], off
	global_load_dwordx4 v[186:189], v[20:21], off offset:16
	v_lshl_add_u64 v[20:21], v[20:21], 0, s[14:15]
	global_load_dwordx4 v[190:193], v[20:21], off
	global_load_dwordx4 v[194:197], v[20:21], off offset:16
	v_lshl_add_u64 v[20:21], v[20:21], 0, s[14:15]
	global_load_dwordx4 v[198:201], v[20:21], off
	global_load_dwordx4 v[202:205], v[20:21], off offset:16
	v_lshl_add_u64 v[20:21], v[20:21], 0, s[14:15]
	global_load_dwordx4 v[206:209], v[20:21], off
	global_load_dwordx4 v[210:213], v[20:21], off offset:16
	v_lshl_add_u64 v[20:21], v[20:21], 0, s[14:15]
	global_load_dwordx4 v[214:217], v[20:21], off
	global_load_dwordx4 v[218:221], v[20:21], off offset:16
	v_lshl_add_u64 v[20:21], v[20:21], 0, s[14:15]
	global_load_dwordx4 v[222:225], v[20:21], off
	global_load_dwordx4 v[226:229], v[20:21], off offset:16
	v_lshlrev_b64 v[22:23], 11, v[40:41]
	v_lshl_add_u64 v[22:23], v[6:7], 0, v[22:23]
	s_mov_b64 s[14:15], 0x1000
	s_waitcnt vmcnt(14)
	v_pk_add_f32 v[136:137], v[104:105], 1.0 op_sel_hi:[1,0]
	v_pk_add_f32 v[138:139], v[106:107], 1.0 op_sel_hi:[1,0]
	v_pk_add_f32 v[140:141], v[108:109], 1.0 op_sel_hi:[1,0]
	v_pk_add_f32 v[142:143], v[110:111], 1.0 op_sel_hi:[1,0]
	v_pk_fma_f32 v[24:25], v[166:167], v[136:137], v[112:113]
	v_pk_fma_f32 v[26:27], v[168:169], v[138:139], v[114:115]
	v_pk_fma_f32 v[28:29], v[170:171], v[140:141], v[116:117]
	v_pk_fma_f32 v[30:31], v[172:173], v[142:143], v[118:119]
	v_cvt_pk_bf16_f32 v16, v24, v25
	v_cvt_pk_bf16_f32 v17, v26, v27
	v_cvt_pk_bf16_f32 v18, v28, v29
	v_cvt_pk_bf16_f32 v19, v30, v31
	global_store_dwordx4 v[22:23], v[16:19], off
	v_lshl_add_u64 v[22:23], v[22:23], 0, s[14:15]
	s_waitcnt vmcnt(13)
	v_pk_fma_f32 v[24:25], v[174:175], v[136:137], v[112:113]
	v_pk_fma_f32 v[26:27], v[176:177], v[138:139], v[114:115]
	v_pk_fma_f32 v[28:29], v[178:179], v[140:141], v[116:117]
	v_pk_fma_f32 v[30:31], v[180:181], v[142:143], v[118:119]
	v_cvt_pk_bf16_f32 v32, v24, v25
	v_cvt_pk_bf16_f32 v33, v26, v27
	v_cvt_pk_bf16_f32 v34, v28, v29
	v_cvt_pk_bf16_f32 v35, v30, v31
	global_store_dwordx4 v[22:23], v[32:35], off
	v_lshl_add_u64 v[22:23], v[22:23], 0, s[14:15]
	s_waitcnt vmcnt(12)
	v_pk_fma_f32 v[24:25], v[182:183], v[136:137], v[112:113]
	v_pk_fma_f32 v[26:27], v[184:185], v[138:139], v[114:115]
	v_pk_fma_f32 v[28:29], v[186:187], v[140:141], v[116:117]
	v_pk_fma_f32 v[30:31], v[188:189], v[142:143], v[118:119]
	v_cvt_pk_bf16_f32 v16, v24, v25
	v_cvt_pk_bf16_f32 v17, v26, v27
	v_cvt_pk_bf16_f32 v18, v28, v29
	v_cvt_pk_bf16_f32 v19, v30, v31
	global_store_dwordx4 v[22:23], v[16:19], off
	v_lshl_add_u64 v[22:23], v[22:23], 0, s[14:15]
	s_waitcnt vmcnt(11)
	v_pk_fma_f32 v[24:25], v[190:191], v[136:137], v[112:113]
	v_pk_fma_f32 v[26:27], v[192:193], v[138:139], v[114:115]
	v_pk_fma_f32 v[28:29], v[194:195], v[140:141], v[116:117]
	v_pk_fma_f32 v[30:31], v[196:197], v[142:143], v[118:119]
	v_cvt_pk_bf16_f32 v32, v24, v25
	v_cvt_pk_bf16_f32 v33, v26, v27
	v_cvt_pk_bf16_f32 v34, v28, v29
	v_cvt_pk_bf16_f32 v35, v30, v31
	global_store_dwordx4 v[22:23], v[32:35], off
	v_lshl_add_u64 v[22:23], v[22:23], 0, s[14:15]
	s_waitcnt vmcnt(10)
	v_pk_fma_f32 v[24:25], v[198:199], v[136:137], v[112:113]
	v_pk_fma_f32 v[26:27], v[200:201], v[138:139], v[114:115]
	v_pk_fma_f32 v[28:29], v[202:203], v[140:141], v[116:117]
	v_pk_fma_f32 v[30:31], v[204:205], v[142:143], v[118:119]
	v_cvt_pk_bf16_f32 v16, v24, v25
	v_cvt_pk_bf16_f32 v17, v26, v27
	v_cvt_pk_bf16_f32 v18, v28, v29
	v_cvt_pk_bf16_f32 v19, v30, v31
	global_store_dwordx4 v[22:23], v[16:19], off
	v_lshl_add_u64 v[22:23], v[22:23], 0, s[14:15]
	s_waitcnt vmcnt(9)
	v_pk_fma_f32 v[24:25], v[206:207], v[136:137], v[112:113]
	v_pk_fma_f32 v[26:27], v[208:209], v[138:139], v[114:115]
	v_pk_fma_f32 v[28:29], v[210:211], v[140:141], v[116:117]
	v_pk_fma_f32 v[30:31], v[212:213], v[142:143], v[118:119]
	v_cvt_pk_bf16_f32 v32, v24, v25
	v_cvt_pk_bf16_f32 v33, v26, v27
	v_cvt_pk_bf16_f32 v34, v28, v29
	v_cvt_pk_bf16_f32 v35, v30, v31
	global_store_dwordx4 v[22:23], v[32:35], off
	v_lshl_add_u64 v[22:23], v[22:23], 0, s[14:15]
	s_waitcnt vmcnt(8)
	v_pk_fma_f32 v[24:25], v[214:215], v[136:137], v[112:113]
	v_pk_fma_f32 v[26:27], v[216:217], v[138:139], v[114:115]
	v_pk_fma_f32 v[28:29], v[218:219], v[140:141], v[116:117]
	v_pk_fma_f32 v[30:31], v[220:221], v[142:143], v[118:119]
	v_cvt_pk_bf16_f32 v16, v24, v25
	v_cvt_pk_bf16_f32 v17, v26, v27
	v_cvt_pk_bf16_f32 v18, v28, v29
	v_cvt_pk_bf16_f32 v19, v30, v31
	global_store_dwordx4 v[22:23], v[16:19], off
	v_lshl_add_u64 v[22:23], v[22:23], 0, s[14:15]
	s_waitcnt vmcnt(7)
	v_pk_fma_f32 v[24:25], v[222:223], v[136:137], v[112:113]
	v_pk_fma_f32 v[26:27], v[224:225], v[138:139], v[114:115]
	v_pk_fma_f32 v[28:29], v[226:227], v[140:141], v[116:117]
	v_pk_fma_f32 v[30:31], v[228:229], v[142:143], v[118:119]
	v_cvt_pk_bf16_f32 v32, v24, v25
	v_cvt_pk_bf16_f32 v33, v26, v27
	v_cvt_pk_bf16_f32 v34, v28, v29
	v_cvt_pk_bf16_f32 v35, v30, v31
	global_store_dwordx4 v[22:23], v[32:35], off
	s_movk_i32 s2, 0x800
	s_mov_b64 s[14:15], 0
